# scan loader waves also convert the square weight tiles (out-proj / S5 GLU / PLE gate with row scale) of the conversion queue
# speedup vs baseline: 1.0027x; 1.0027x over previous
.Lcv_w1:
	s_cmp_lt_u32 s94, 2
	s_cbranch_scc1 .Lcv_b_notitem
	s_cmp_eq_u32 s94, 2
	s_cbranch_scc1 .Lcv_b_scale
	s_cmp_eq_u32 s94, 5
	s_cbranch_scc0 .Lcv_b_cvt
.Lcv_b_scale:
	v_pk_mul_f32 v[130:131], v[130:131], v[162:163] op_sel_hi:[1,0]
	v_pk_mul_f32 v[132:133], v[132:133], v[162:163] op_sel_hi:[1,0]
	v_pk_mul_f32 v[134:135], v[134:135], v[162:163] op_sel:[0,1] op_sel_hi:[1,1]
	v_pk_mul_f32 v[136:137], v[136:137], v[162:163] op_sel:[0,1] op_sel_hi:[1,1]
	v_pk_mul_f32 v[138:139], v[138:139], v[164:165] op_sel_hi:[1,0]
	v_pk_mul_f32 v[140:141], v[140:141], v[164:165] op_sel_hi:[1,0]
	v_pk_mul_f32 v[142:143], v[142:143], v[164:165] op_sel:[0,1] op_sel_hi:[1,1]
	v_pk_mul_f32 v[144:145], v[144:145], v[164:165] op_sel:[0,1] op_sel_hi:[1,1]
	v_pk_mul_f32 v[146:147], v[146:147], v[166:167] op_sel_hi:[1,0]
	v_pk_mul_f32 v[148:149], v[148:149], v[166:167] op_sel_hi:[1,0]
	v_pk_mul_f32 v[150:151], v[150:151], v[166:167] op_sel:[0,1] op_sel_hi:[1,1]
	v_pk_mul_f32 v[152:153], v[152:153], v[166:167] op_sel:[0,1] op_sel_hi:[1,1]
	v_pk_mul_f32 v[154:155], v[154:155], v[168:169] op_sel_hi:[1,0]
	v_pk_mul_f32 v[156:157], v[156:157], v[168:169] op_sel_hi:[1,0]
	v_pk_mul_f32 v[158:159], v[158:159], v[168:169] op_sel:[0,1] op_sel_hi:[1,1]
	v_pk_mul_f32 v[160:161], v[160:161], v[168:169] op_sel:[0,1] op_sel_hi:[1,1]
.Lcv_b_cvt:
	v_cvt_pk_bf16_f32 v174, v130, v134
	v_cvt_pk_bf16_f32 v175, v138, v142
	v_cvt_pk_bf16_f32 v176, v146, v150
	v_cvt_pk_bf16_f32 v177, v154, v158
	v_cvt_pk_bf16_f32 v178, v131, v135
	v_cvt_pk_bf16_f32 v179, v139, v143
	v_cvt_pk_bf16_f32 v180, v147, v151
	v_cvt_pk_bf16_f32 v181, v155, v159
	v_cvt_pk_bf16_f32 v182, v132, v136
	v_cvt_pk_bf16_f32 v183, v140, v144
	v_cvt_pk_bf16_f32 v184, v148, v152
	v_cvt_pk_bf16_f32 v185, v156, v160
	v_cvt_pk_bf16_f32 v186, v133, v137
	v_cvt_pk_bf16_f32 v187, v141, v145
	v_cvt_pk_bf16_f32 v188, v149, v153
	v_cvt_pk_bf16_f32 v189, v157, v161
	s_cmp_eq_u32 s94, 3
	s_cbranch_scc1 .Lcv_b_st1
	global_store_dwordx4 v108, v[174:177], s[96:97]
	s_add_u32 s96, s96, 0x1000
	s_addc_u32 s97, s97, 0
	s_nop 0
	global_store_dwordx4 v108, v[178:181], s[96:97]
	s_add_u32 s96, s96, 0x1000
	s_addc_u32 s97, s97, 0
	s_nop 0
	global_store_dwordx4 v108, v[182:185], s[96:97]
	s_add_u32 s96, s96, 0x1000
	s_addc_u32 s97, s97, 0
	s_nop 0
	global_store_dwordx4 v108, v[186:189], s[96:97]
	s_branch .Lcv_b_done

.Lcv_mid:
	s_cmp_lt_i32 s3, 0xffffff00
	s_cbranch_scc1 .Lcv_sqG
	s_branch .Lcv_a_blocked
.Lcv_sqA:
	s_add_i32 s3, s3, 0x800
	s_lshr_b32 s2, s4, 1
	s_lshl_b32 s61, s2, 24
	s_lshl_b32 s66, s2, 23
	s_and_b32 s2, s4, 1
	s_mul_i32 s5, s2, 0x48
	s_add_i32 s5, s5, 0x148
	s_lshl_b32 s2, s2, 24
	s_add_u32 s66, s66, s2
	s_add_u32 s66, s66, 0x26200000
	s_mov_b32 s18, 0
	s_branch .Lcv_sq
.Lcv_sqG:
	s_add_i32 s3, s3, 0x900
	s_lshl_b32 s61, s4, 24
	s_lshl_b32 s66, s4, 23
	s_add_u32 s66, s66, 0x21200000
	s_movk_i32 s5, 0xa0
	s_lshl_b32 s62, s4, 13
	s_mov_b32 s18, 1
.Lcv_sq:
	s_lshr_b32 s91, s3, 6
	s_and_b32 s2, s3, 63
	s_lshl_b32 s56, s91, 19
	s_add_u32 s61, s61, s56
	s_lshl_b32 s56, s2, 7
	s_add_u32 s61, s61, s56
	s_lshl_b32 s56, s2, 17
	s_add_u32 s66, s66, s56
	s_lshl_b32 s56, s91, 7
	s_add_u32 s66, s66, s56
	s_load_dwordx2 s[32:33], s[0:1], s5
	s_load_dwordx2 s[98:99], s[0:1], 0x1b0
	s_cmp_eq_u32 s18, 0
	s_cbranch_scc1 .Lcv_sq_ns
	s_lshl_b32 s56, s91, 8
	s_add_i32 s62, s62, s56
	s_load_dwordx2 s[2:3], s[0:1], 0x98
	s_waitcnt lgkmcnt(0)
	s_add_u32 s2, s2, s62
	s_addc_u32 s3, s3, 0
	s_nop 0
	global_load_dwordx4 v[162:165], v110, s[2:3]
	global_load_dwordx4 v[166:169], v110, s[2:3] offset:16
	s_mov_b32 s94, 5
	s_branch .Lcv_sq_ld
.Lcv_sq_ns:
	s_waitcnt lgkmcnt(0)
	s_mov_b32 s94, 4
.Lcv_sq_ld:
	s_add_u32 s32, s32, s61
	s_addc_u32 s33, s33, 0
	s_add_u32 s96, s98, s66
	s_addc_u32 s97, s99, 0
	s_nop 0
	global_load_dwordx4 v[130:133], v107, s[32:33] nt
	s_add_u32 s32, s32, 0x2000
	s_addc_u32 s33, s33, 0
	s_nop 0
	global_load_dwordx4 v[134:137], v107, s[32:33] nt
	s_add_u32 s32, s32, 0x2000
	s_addc_u32 s33, s33, 0
	s_nop 0
	global_load_dwordx4 v[138:141], v107, s[32:33] nt
	s_add_u32 s32, s32, 0x2000
	s_addc_u32 s33, s33, 0
	s_nop 0
	global_load_dwordx4 v[142:145], v107, s[32:33] nt
	s_add_u32 s32, s32, 0x2000
	s_addc_u32 s33, s33, 0
	s_nop 0
	global_load_dwordx4 v[146:149], v107, s[32:33] nt
	s_add_u32 s32, s32, 0x2000
	s_addc_u32 s33, s33, 0
	s_nop 0
	global_load_dwordx4 v[150:153], v107, s[32:33] nt
	s_add_u32 s32, s32, 0x2000
	s_addc_u32 s33, s33, 0
	s_nop 0
	global_load_dwordx4 v[154:157], v107, s[32:33] nt
	s_add_u32 s32, s32, 0x2000
	s_addc_u32 s33, s33, 0
	s_nop 0
	global_load_dwordx4 v[158:161], v107, s[32:33] nt
	s_add_i32 s92, s92, 1
	s_sub_i32 s93, s93, 1
	s_cmp_eq_u32 s94, 5
	s_cbranch_scc1 .Lcv_pad0
	s_branch .Lcv_pad2
